# tile remap variant: the non-table 6-unit workgroups take 2 expensive tiles, the S5-table workgroups 4 and 3
# baseline (speedup 1.0000x reference)
.LBB0_68:
	s_or_b64 exec, exec, s[4:5]
	s_add_u32 s14, s24, 0xda40000
	s_addc_u32 s15, s25, 0
	v_writelane_b32 v251, s14, 10
	s_add_u32 s4, s24, 0xfa40000
	s_addc_u32 s5, s25, 0
	v_writelane_b32 v251, s15, 11
	v_writelane_b32 v251, s4, 12
	v_mov_b32_e32 v1, 0
	v_add_u32_e32 v215, 0xfffffe00, v200
	v_writelane_b32 v251, s5, 13
	s_add_u32 s4, s24, 0x13a40000
	s_addc_u32 s5, s25, 0
	s_add_u32 s16, s24, 0x20e40000
	s_addc_u32 s17, s25, 0
	s_add_u32 s18, s24, 0x21e40000
	s_addc_u32 s19, s25, 0
	s_add_u32 s20, s24, 0x24e40000
	s_addc_u32 s21, s25, 0
	s_ashr_i32 s55, s54, 31
	v_writelane_b32 v251, s4, 14
	s_cmpk_lt_i32 s54, 0x6a0
	s_cselect_b64 s[22:23], -1, 0
	v_writelane_b32 v251, s5, 15
	s_add_u32 s4, s24, 0x26e40000
	v_writelane_b32 v251, s4, 16
	s_addc_u32 s4, s25, 0
	v_writelane_b32 v251, s4, 17
	s_add_u32 s4, s24, 0x27e40000
	s_addc_u32 s5, s25, 0
	v_writelane_b32 v251, s4, 18
	v_lshlrev_b32_e32 v218, 2, v200
	v_mov_b32_e32 v219, 0x358637bd
	v_writelane_b32 v251, s5, 19
	s_add_u32 s4, s24, 0x28040000
	v_writelane_b32 v251, s4, 20
	s_addc_u32 s4, s25, 0
	v_writelane_b32 v251, s4, 21
	s_add_u32 s4, s24, 0xda20000
	s_addc_u32 s5, s25, 0
	v_writelane_b32 v251, s4, 22
	v_mov_b32_e32 v220, 0x260
	v_mov_b32_e32 v221, 1
	v_writelane_b32 v251, s5, 23
	s_add_u32 s4, s24, 0x28064000
	v_writelane_b32 v251, s4, 24
	s_addc_u32 s4, s25, 0
	v_writelane_b32 v251, s4, 25
	s_add_u32 s4, s24, 0x28074000
	s_addc_u32 s5, s25, 0
	v_writelane_b32 v251, s4, 26
	v_mov_b64_e32 v[202:203], 0x6a0
	v_mov_b64_e32 v[204:205], 0x69f
	v_writelane_b32 v251, s5, 27
	s_not_b32 s4, s54
	s_add_i32 s10, s26, s4
	s_cmp_lt_i32 s10, 64
	s_cselect_b64 s[4:5], -1, 0
	v_writelane_b32 v251, s4, 28
	v_mbcnt_hi_u32_b32 v217, -1, v50
	v_mov_b32_e32 v222, 0xfffa0000
	v_writelane_b32 v251, s5, 29
	s_lshr_b32 s4, s55, 29
	s_add_i32 s4, s54, s4
	s_ashr_i32 s5, s4, 3
	s_and_b32 s4, s4, -8
	s_sub_i32 s6, s54, s4
	s_add_u32 s4, s24, 0x9600000
	v_writelane_b32 v251, s4, 30
	s_addc_u32 s4, s25, 0
	v_writelane_b32 v251, s4, 31
	s_add_u32 s4, s24, 0x9a10000
	v_writelane_b32 v251, s4, 32
	s_addc_u32 s4, s25, 0
	v_writelane_b32 v251, s4, 33
	s_add_u32 s4, s24, 0xba10000
	v_writelane_b32 v251, s4, 34
	s_addc_u32 s4, s25, 0
	v_writelane_b32 v251, s4, 35
	s_add_u32 s4, s24, 0xda10000
	v_writelane_b32 v251, s4, 36
	s_addc_u32 s4, s25, 0
	v_writelane_b32 v251, s4, 37
	s_add_i32 s4, 0, 0x20040
	s_ashr_i32 s7, s26, 31
	s_add_u32 s12, s24, 0x28060200
	s_addc_u32 s13, s25, 0
	v_writelane_b32 v251, s7, 38
	s_add_u32 s34, s24, 0x28060400
	v_writelane_b32 v251, s12, 39
	s_addc_u32 s35, s25, 0
	v_lshl_add_u32 v214, v200, 2, s4
	v_writelane_b32 v251, s13, 40
	s_add_u32 s12, s24, 0x28060500
	s_addc_u32 s13, s25, 0
	v_writelane_b32 v251, s12, 41
	v_mov_b32_e32 v223, 0xf149f2ca
	v_mov_b64_e32 v[206:207], 0x80
	v_writelane_b32 v251, s13, 42
	s_add_u32 s12, s24, 0x28060600
	s_addc_u32 s13, s25, 0
	v_writelane_b32 v251, s12, 43
	v_mov_b64_e32 v[208:209], 0x7f
	v_mov_b64_e32 v[210:211], 0x100
	v_writelane_b32 v251, s13, 44
	s_add_u32 s12, s24, 0x28060700
	s_addc_u32 s13, s25, 0
	v_writelane_b32 v251, s12, 45
	v_mov_b64_e32 v[212:213], 0xff
	s_movk_i32 s78, 0x6a00
	v_writelane_b32 v251, s13, 46
	s_add_u32 s12, s24, 0x28060800
	s_addc_u32 s13, s25, 0
	v_writelane_b32 v251, s12, 47
	s_nop 1
	v_writelane_b32 v251, s13, 48
	s_add_u32 s12, s24, 0x28060900
	s_addc_u32 s13, s25, 0
	v_writelane_b32 v251, s12, 49
	s_nop 1
	v_writelane_b32 v251, s13, 50
	s_add_u32 s12, s24, 0x28060a00
	s_addc_u32 s13, s25, 0
	v_writelane_b32 v251, s12, 51
	s_nop 1
	v_writelane_b32 v251, s13, 52
	s_add_u32 s12, s24, 0x28060b00
	s_addc_u32 s13, s25, 0
	v_writelane_b32 v251, s12, 53
	s_nop 1
	v_writelane_b32 v251, s13, 54
	s_add_u32 s12, s24, 0x28060c00
	s_addc_u32 s13, s25, 0
	v_writelane_b32 v251, s12, 55
	s_nop 1
	v_writelane_b32 v251, s13, 56
	s_add_u32 s12, s24, 0x28060d00
	s_addc_u32 s13, s25, 0
	v_writelane_b32 v251, s12, 57
	s_nop 1
	v_writelane_b32 v251, s13, 58
	s_add_u32 s12, s24, 0x28060e00
	s_addc_u32 s13, s25, 0
	v_writelane_b32 v251, s12, 59
	s_nop 1
	v_writelane_b32 v251, s13, 60
	s_add_u32 s12, s24, 0x28060f00
	s_addc_u32 s13, s25, 0
	v_writelane_b32 v251, s12, 61
	s_nop 1
	v_writelane_b32 v251, s13, 62
	s_add_u32 s12, s24, 0x28061000
	s_addc_u32 s13, s25, 0
	v_writelane_b32 v251, s12, 63
	s_nop 1
	v_writelane_b32 v252, s13, 0
	s_add_u32 s12, s24, 0x28061100
	s_addc_u32 s13, s25, 0
	v_writelane_b32 v252, s12, 1
	s_nop 1
	v_writelane_b32 v252, s13, 2
	s_add_u32 s12, s24, 0x28061200
	s_addc_u32 s13, s25, 0
	v_writelane_b32 v252, s12, 3
	s_nop 1
	v_writelane_b32 v252, s13, 4
	s_add_u32 s12, s24, 0x28061300
	s_addc_u32 s13, s25, 0
	v_writelane_b32 v252, s12, 5
	s_cmp_eq_u32 s8, 15
	s_nop 0
	v_writelane_b32 v252, s13, 6
	s_cselect_b64 s[12:13], -1, 0
	v_writelane_b32 v252, s12, 7
	s_cmp_eq_u32 s8, 14
	s_nop 0
	v_writelane_b32 v252, s13, 8
	s_cselect_b64 s[12:13], -1, 0
	v_writelane_b32 v252, s12, 9
	s_cmp_eq_u32 s8, 13
	s_nop 0
	v_writelane_b32 v252, s13, 10
	s_cselect_b64 s[12:13], -1, 0
	v_writelane_b32 v252, s12, 11
	s_cmp_eq_u32 s8, 12
	s_nop 0
	v_writelane_b32 v252, s13, 12
	s_cselect_b64 s[12:13], -1, 0
	v_writelane_b32 v252, s12, 13
	s_cmp_eq_u32 s8, 11
	s_nop 0
	v_writelane_b32 v252, s13, 14
	s_cselect_b64 s[12:13], -1, 0
	v_writelane_b32 v252, s12, 15
	s_cmp_eq_u32 s8, 10
	s_nop 0
	v_writelane_b32 v252, s13, 16
	s_cselect_b64 s[12:13], -1, 0
	v_writelane_b32 v252, s12, 17
	s_cmp_eq_u32 s8, 9
	s_nop 0
	v_writelane_b32 v252, s13, 18
	s_cselect_b64 s[12:13], -1, 0
	v_writelane_b32 v252, s12, 19
	s_cmp_eq_u32 s8, 8
	s_nop 0
	v_writelane_b32 v252, s13, 20
	s_cselect_b64 s[12:13], -1, 0
	v_writelane_b32 v252, s12, 21
	s_cmp_eq_u32 s8, 7
	s_nop 0
	v_writelane_b32 v252, s13, 22
	s_cselect_b64 s[12:13], -1, 0
	v_writelane_b32 v252, s12, 23
	s_cmp_eq_u32 s8, 6
	s_nop 0
	v_writelane_b32 v252, s13, 24
	s_cselect_b64 s[12:13], -1, 0
	v_writelane_b32 v252, s12, 25
	s_cmp_eq_u32 s8, 5
	s_nop 0
	v_writelane_b32 v252, s13, 26
	s_cselect_b64 s[12:13], -1, 0
	v_writelane_b32 v252, s12, 27
	s_cmp_eq_u32 s8, 4
	s_nop 0
	v_writelane_b32 v252, s13, 28
	s_cselect_b64 s[12:13], -1, 0
	v_writelane_b32 v252, s12, 29
	s_cmp_eq_u32 s8, 3
	s_nop 0
	v_writelane_b32 v252, s13, 30
	s_cselect_b64 s[12:13], -1, 0
	v_writelane_b32 v252, s12, 31
	s_cmp_eq_u32 s8, 2
	s_nop 0
	v_writelane_b32 v252, s13, 32
	s_cselect_b64 s[12:13], -1, 0
	v_writelane_b32 v252, s12, 33
	s_cmp_eq_u32 s8, 1
	s_nop 0
	v_writelane_b32 v252, s13, 34
	s_cselect_b64 s[12:13], -1, 0
	v_writelane_b32 v252, s12, 35
	s_cmp_eq_u32 s8, 0
	s_nop 0
	v_writelane_b32 v252, s13, 36
	s_cselect_b64 s[12:13], -1, 0
	s_lshl_b32 s7, s9, 2
	s_add_u32 s2, s2, s7
	s_addc_u32 s3, s3, 0
	v_writelane_b32 v252, s12, 37
	s_add_u32 s8, s2, 0x1400
	s_addc_u32 s9, s3, 0
	v_writelane_b32 v252, s13, 38
	v_writelane_b32 v252, s8, 39
	s_add_u32 s2, s2, 0x2400
	s_addc_u32 s3, s3, 0
	v_writelane_b32 v252, s9, 40
	v_writelane_b32 v252, s2, 41
	s_nop 1
	v_writelane_b32 v252, s3, 42
	s_add_u32 s2, s24, 0x28063400
	s_addc_u32 s3, s25, 0
	v_writelane_b32 v252, s2, 43
	s_nop 1
	v_writelane_b32 v252, s3, 44
	s_add_u32 s2, s24, 0x28063500
	s_addc_u32 s3, s25, 0
	v_writelane_b32 v252, s2, 45
	s_cmpk_lt_i32 s54, 0x300
	s_nop 0
	v_writelane_b32 v252, s3, 46
	s_cselect_b64 s[2:3], -1, 0
	v_writelane_b32 v252, s2, 47
	s_nop 1
	v_writelane_b32 v252, s3, 48
	s_add_u32 s2, s24, 0x26e40000
	s_addc_u32 s3, s25, 0
	v_writelane_b32 v252, s2, 49
	s_nop 1
	v_writelane_b32 v252, s3, 50
	s_add_u32 s2, s24, 0x28040000
	v_writelane_b32 v252, s2, 51
	s_addc_u32 s2, s25, 0
	v_writelane_b32 v252, s2, 52
	s_add_u32 s2, s24, 0x13a40000
	s_addc_u32 s3, s25, 0
	v_writelane_b32 v252, s2, 53
	s_nop 1
	v_writelane_b32 v252, s3, 54
	s_add_u32 s2, s24, 0x22e40000
	s_addc_u32 s3, s25, 0
	v_writelane_b32 v252, s2, 55
	s_nop 1
	v_writelane_b32 v252, s3, 56
	s_add_u32 s2, s24, 0x28074000
	s_addc_u32 s3, s25, 0
	v_writelane_b32 v252, s2, 57
	s_nop 1
	v_writelane_b32 v252, s3, 58
	s_add_u32 s2, s24, 0x20e40000
	v_writelane_b32 v252, s2, 59
	s_addc_u32 s2, s25, 0
	s_cmpk_gt_i32 s54, 0x7f
	v_writelane_b32 v252, s2, 60
	s_cselect_b32 s2, s10, 0x100
	s_add_i32 s3, s26, 0xffffff80
	s_cmpk_gt_i32 s26, 0x80
	s_cselect_b32 s13, s2, s54
	s_cselect_b32 s28, s3, s26
	s_cmpk_lt_i32 s13, 0x100
	v_writelane_b32 v252, s10, 61
	s_cselect_b64 s[2:3], -1, 0
	v_writelane_b32 v252, s2, 62
	s_nop 1
	v_writelane_b32 v252, s3, 63
	s_add_u32 s2, s24, 0x6a00000
	v_writelane_b32 v253, s2, 0
	s_addc_u32 s2, s25, 0
	s_cmp_gt_i32 s54, -1
	s_cselect_b32 s29, s54, 0x100000
	s_cmpk_lt_u32 s29, 0x80
	v_writelane_b32 v253, s2, 1
	s_cselect_b64 s[2:3], -1, 0
	v_writelane_b32 v253, s2, 2
	s_nop 1
	v_writelane_b32 v253, s3, 3
	s_lshl_b32 s2, s29, 2
	s_and_b32 s2, s2, 28
	s_add_u32 s3, s24, 0x6e00000
	v_writelane_b32 v253, s3, 4
	s_addc_u32 s3, s25, 0
	s_cmpk_lt_i32 s54, 0x100
	v_writelane_b32 v253, s3, 5
	s_cselect_b64 s[8:9], -1, 0
	v_writelane_b32 v253, s8, 6
	s_lshl_b32 s3, s6, 5
	s_add_u32 s7, s24, 0x8600000
	v_writelane_b32 v253, s9, 7
	s_load_dwordx4 s[8:11], s[0:1], 0x0
	v_writelane_b32 v253, s7, 8
	s_addc_u32 s7, s25, 0
	v_writelane_b32 v253, s7, 9
	s_movk_i32 s7, 0xd5
	s_waitcnt lgkmcnt(0)
	s_add_u32 s10, s10, 0x2000
	v_writelane_b32 v253, s8, 10
	s_nop 1
	v_writelane_b32 v253, s9, 11
	v_writelane_b32 v253, s10, 12
	v_writelane_b32 v253, s11, 13
	s_addc_u32 s11, s11, 0
	s_add_u32 s8, s24, 0x2806c000
	s_addc_u32 s9, s25, 0
	s_cmp_lt_i32 s6, 0
	s_cselect_b32 s7, s7, 0xd4
	v_writelane_b32 v253, s10, 14
	s_mul_i32 s7, s6, s7
	s_mul_i32 s6, s6, 33
	v_writelane_b32 v253, s11, 15
	s_cselect_b32 s3, s6, s3
	s_add_i32 s7, s7, s5
	v_writelane_b32 v253, s8, 16
	s_mul_hi_i32 s6, s7, 0x4d4873ed
	s_nop 0
	v_writelane_b32 v253, s9, 17
	s_lshr_b32 s8, s6, 31
	s_ashr_i32 s6, s6, 6
	s_add_i32 s6, s6, s8
	s_mul_i32 s8, s6, 0xd4
	s_sub_i32 s8, s7, s8
	s_bfe_u32 s7, s8, 0x2001d
	s_add_i32 s7, s8, s7
	s_sext_i32_i16 s9, s7
	s_ashr_i32 s9, s9, 2
	s_mul_i32 s10, s6, 7
	s_add_i32 s10, s10, s9
	s_mul_hi_i32 s9, s10, 0x4d4873ed
	s_lshr_b32 s11, s9, 31
	s_ashr_i32 s9, s9, 4
	s_add_i32 s9, s9, s11
	s_bfe_u32 s11, s29, 0x20003
	s_or_b32 s30, s2, s11
	s_lshl_b32 s11, s6, 2
	s_sub_i32 s2, 32, s11
	s_min_i32 s12, s2, 4
	s_and_b32 s2, s7, 0xfffc
	s_sub_i32 s2, s8, s2
	v_writelane_b32 v253, s29, 18
	s_sext_i32_i16 s2, s2
	s_mul_i32 s9, s9, 53
	s_bfe_u32 s6, s29, 0x60005
	v_writelane_b32 v253, s30, 19
	s_sub_i32 s36, s10, s9
	v_readlane_b32 s98, v251, 0
	s_nop 3
	s_and_b32 s99, s98, 7
	s_lshr_b32 s98, s98, 5
	s_cmp_lt_u32 s98, 5
	s_cbranch_scc1 .Lmp0_A
	s_sub_i32 s98, s98, 3
	s_cmp_ge_u32 s98, 3
	s_cbranch_scc0 .Lmp0_P
	s_sub_i32 s98, s98, 3
.Lmp0_P:
	s_add_i32 s98, s98, 5
	s_sub_i32 vcc_lo, 9, s98
	s_mov_b32 vcc_lo, s99
	s_cmp_eq_u32 s98, 5
	s_cbranch_scc0 .Lmp0_H6
	s_and_b32 s36, vcc_lo, 1
	s_and_b32 vcc_lo, vcc_lo, 2
	s_lshl_b32 vcc_lo, vcc_lo, 2
	s_add_i32 s36, s36, vcc_lo
	s_add_i32 s36, s36, 12
	s_branch .Lmp0_D

.LBB0_114:
	s_add_i32 s74, s74, 1
	v_readlane_b32 s17, v251, 38
	s_mul_i32 s17, s74, s17
	s_mul_hi_u32 s19, s74, s26
	s_add_i32 s19, s19, s17
	s_mul_i32 s17, s74, s26
	s_add_u32 s20, s17, s54
	s_addc_u32 s21, s19, s55
	v_cmp_gt_i64_e32 vcc, s[20:21], v[204:205]
	v_cmp_lt_i64_e64 s[40:41], s[20:21], v[202:203]
	s_cbranch_vccnz .LBB0_116
	s_ashr_i32 s16, s20, 31
	s_lshr_b32 s16, s16, 29
	s_add_i32 s16, s20, s16
	s_ashr_i32 s17, s16, 3
	s_and_b32 s16, s16, -8
	s_sub_i32 s16, s20, s16
	s_cmp_lt_i32 s16, 0
	s_movk_i32 s18, 0xd5
	s_cselect_b32 s18, s18, 0xd4
	s_mul_i32 s16, s16, s18
	s_add_i32 s16, s16, s17
	s_mul_hi_i32 s17, s16, 0x4d4873ed
	s_lshr_b32 s18, s17, 31
	s_ashr_i32 s17, s17, 6
	s_add_i32 s17, s17, s18
	s_lshl_b32 s18, s17, 2
	s_sub_i32 s19, 32, s18
	s_min_i32 s19, s19, 4
	s_abs_i32 s20, s19
	v_cvt_f32_u32_e32 v0, s20
	s_sub_i32 s28, 0, s20
	s_mul_i32 s21, s17, 0xd4
	s_sub_i32 s16, s16, s21
	v_rcp_iflag_f32_e32 v0, v0
	s_abs_i32 s21, s16
	s_xor_b32 s27, s16, s19
	s_ashr_i32 s27, s27, 31
	v_mul_f32_e32 v0, 0x4f7ffffe, v0
	v_cvt_u32_f32_e32 v0, v0
	s_mul_i32 s17, s17, 7
	v_readfirstlane_b32 s29, v0
	s_mul_i32 s28, s28, s29
	s_mul_hi_u32 s28, s29, s28
	s_add_i32 s29, s29, s28
	s_mul_hi_u32 s28, s21, s29
	s_mul_i32 s29, s28, s20
	s_sub_i32 s21, s21, s29
	s_add_i32 s33, s28, 1
	s_sub_i32 s29, s21, s20
	s_cmp_ge_u32 s21, s20
	s_cselect_b32 s28, s33, s28
	s_cselect_b32 s21, s29, s21
	s_add_i32 s29, s28, 1
	s_cmp_ge_u32 s21, s20
	s_cselect_b32 s20, s29, s28
	s_xor_b32 s20, s20, s27
	s_sub_i32 s20, s20, s27
	s_mul_i32 s19, s20, s19
	s_sub_i32 s16, s16, s19
	s_add_i32 s17, s17, s20
	s_add_i32 s16, s18, s16
	s_mul_hi_i32 s18, s17, 0x4d4873ed
	s_lshr_b32 s19, s18, 31
	s_ashr_i32 s18, s18, 4
	s_add_i32 s18, s18, s19
	s_mul_i32 s18, s18, 53
	s_sub_i32 s18, s17, s18
	v_readlane_b32 s17, v251, 0
	s_nop 3
	s_and_b32 s19, s17, 7
	s_lshr_b32 s17, s17, 5
	s_cmp_lt_u32 s17, 5
	s_cbranch_scc1 .Lmp1_A
	s_sub_i32 s17, s17, 3
	s_cmp_ge_u32 s17, 3
	s_cbranch_scc0 .Lmp1_P
	s_sub_i32 s17, s17, 3
.Lmp1_P:
	s_add_i32 s17, s17, 5
	s_sub_i32 s20, 9, s17
	s_cmp_lt_u32 s74, s20
	s_cbranch_scc1 .Lmp1_H
	s_sub_i32 s21, s74, s20
	s_sub_i32 s20, s17, 5
	s_lshl_b32 s18, s20, 1
	s_lshr_b32 s20, s20, 1
	s_add_i32 s18, s18, s20
	s_add_i32 s18, s18, s21
	s_add_i32 s18, s18, 35
	s_branch .Lmp1_L
